# attention fast loops: peeled steady-state body (step counter < 60) with all counter guards, selects and wait selection resolved statically; guarded body runs the tail
# speedup vs baseline: 1.0162x; 1.0045x over previous
.LBB0_914:
	s_cmp_lt_u32 s47, 60
	s_cbranch_scc1 .Lst1
	s_cmpk_lt_u32 s47, 0x41
	s_cselect_b64 s[2:3], -1, 0
	s_cmp_gt_u32 s47, 64
	s_cselect_b64 s[42:43], -1, 0
	s_and_b64 vcc, exec, s[42:43]
	s_cbranch_vccnz .LBB0_916
	s_cmp_lt_u32 s47, 61
	s_cselect_b32 s44, s40, s21
	s_add_i32 s44, s44, s41
	s_sub_i32 s44, s44, 64
	s_mul_hi_i32 s45, s44, 0x600
	s_mulk_i32 s44, 0x600
	s_add_u32 s44, s14, s44
	s_addc_u32 s45, s15, s45
	s_lshl_b32 s49, s48, 14
	s_add_i32 s49, s58, s49
	s_mov_b32 m0, s49
	s_nop 0
	global_load_lds_dwordx4 v198, s[44:45]
	s_add_i32 m0, s49, 0x400
	s_nop 0
	global_load_lds_dwordx4 v194, s[44:45]

.LBB0_936:
	s_cmp_lt_u32 s21, 60
	s_cbranch_scc1 .Lst0
	s_cmpk_lt_u32 s21, 0x41
	s_cselect_b64 s[44:45], -1, 0
	s_cmp_gt_u32 s21, 64
	s_cselect_b64 s[42:43], -1, 0
	s_and_b64 vcc, exec, s[42:43]
	s_cbranch_vccnz .LBB0_938
	s_cmp_lt_u32 s21, 61
	s_cselect_b32 s2, s40, s14
	s_add_i32 s2, s2, s15
	s_sub_i32 s2, s2, 64
	s_mul_hi_i32 s3, s2, 0x600
	s_mulk_i32 s2, 0x600
	s_add_u32 s2, s12, s2
	s_addc_u32 s3, s13, s3
	s_lshl_b32 s46, s41, 14
	s_add_i32 s46, s58, s46
	s_mov_b32 m0, s46
	s_nop 0
	global_load_lds_dwordx4 v198, s[2:3]
	s_add_i32 m0, s46, 0x400
	s_nop 0
	global_load_lds_dwordx4 v194, s[2:3]

.Lst0:
	s_mov_b32 s2, s40
	s_add_i32 s2, s2, s15
	s_sub_i32 s2, s2, 64
	s_mul_hi_i32 s3, s2, 0x600
	s_mulk_i32 s2, 0x600
	s_add_u32 s2, s12, s2
	s_addc_u32 s3, s13, s3
	s_lshl_b32 s46, s41, 14
	s_add_i32 s46, s58, s46
	s_mov_b32 m0, s46
	s_nop 0
	global_load_lds_dwordx4 v198, s[2:3]
	s_add_i32 m0, s46, 0x400
	s_nop 0
	global_load_lds_dwordx4 v194, s[2:3]
	s_mov_b32 s46, s40
	s_add_i32 s46, s46, s15
	s_addk_i32 s46, 0xff80
	s_ashr_i32 s47, s46, 31
	s_lshl_b64 s[46:47], s[46:47], 1
	s_add_u32 s46, s39, s46
	s_addc_u32 s47, s67, s47
	s_add_i32 s48, s20, 0xffffc000
	s_and_b32 s48, s48, 0x8000
	s_add_i32 s48, s58, s48
	s_add_i32 m0, s48, 0xc000
	s_nop 0
	global_load_lds_dwordx4 v196, s[46:47]
	s_add_i32 m0, s48, 0xc400
	s_nop 0
	global_load_lds_dwordx4 v192, s[46:47]
	s_add_i32 s46, s41, 1
	s_cmp_lg_u32 s41, 2
	s_cselect_b32 s41, s46, 0
	s_lshl_b32 s46, s41, 14
	s_add_i32 s49, s46, 0
	s_add_i32 s46, s20, 0xffff4000
	v_add_u32_e32 v100, s49, v205
	ds_read_b128 v[96:99], v100
	ds_read_b128 v[100:103], v100 offset:8192
	s_waitcnt lgkmcnt(0)
	v_mfma_f32_32x32x16_bf16 v[112:127], v[96:99], v[160:163], 0
	v_xad_u32 v104, v205, 32, s49
	ds_read_b128 v[128:131], v104
	ds_read_b128 v[132:135], v104 offset:8192
	v_xad_u32 v96, v205, 64, s49
	ds_read_b128 v[136:139], v96
	s_and_b32 s46, s46, 0x8000
	s_add_i32 s48, s46, 0
	v_exp_f32_e32 v140, v48
	v_exp_f32_e32 v141, v49
	v_exp_f32_e32 v142, v50
	v_exp_f32_e32 v143, v51
	ds_read_b128 v[48:51], v96 offset:8192
	v_mfma_f32_32x32x16_bf16 v[96:111], v[100:103], v[160:163], 0
	v_exp_f32_e32 v144, v52
	v_exp_f32_e32 v145, v53
	v_exp_f32_e32 v146, v54
	v_exp_f32_e32 v147, v55
	s_waitcnt lgkmcnt(0)
	v_mfma_f32_32x32x16_bf16 v[112:127], v[128:131], v[164:167], v[112:127]
	v_add_u32_e32 v152, s49, v213
	ds_read_b128 v[52:55], v152
	v_exp_f32_e32 v148, v56
	v_exp_f32_e32 v149, v57
	v_exp_f32_e32 v150, v58
	v_exp_f32_e32 v151, v59
	v_mfma_f32_32x32x16_bf16 v[96:111], v[132:135], v[164:167], v[96:111]
	ds_read_b128 v[56:59], v152 offset:8192
	v_exp_f32_e32 v128, v60
	v_exp_f32_e32 v129, v61
	v_exp_f32_e32 v130, v62
	v_exp_f32_e32 v131, v63
	v_mfma_f32_32x32x16_bf16 v[112:127], v[136:139], v[168:171], v[112:127]
	v_add_u32_e32 v156, s48, v206
	ds_read_b128 v[60:63], v156 offset:49152
	v_exp_f32_e32 v132, v32
	v_exp_f32_e32 v133, v33
	v_exp_f32_e32 v134, v34
	v_exp_f32_e32 v135, v35
	v_mfma_f32_32x32x16_bf16 v[96:111], v[48:51], v[168:171], v[96:111]
	ds_read_b128 v[32:35], v156 offset:53248
	v_exp_f32_e32 v136, v36
	v_exp_f32_e32 v137, v37
	v_exp_f32_e32 v138, v38
	v_exp_f32_e32 v139, v39
	s_waitcnt lgkmcnt(0)
	v_mfma_f32_32x32x16_bf16 v[112:127], v[52:55], v[172:175], v[112:127]
	ds_read_b128 v[36:39], v156 offset:57344
	v_exp_f32_e32 v152, v40
	v_exp_f32_e32 v153, v41
	v_exp_f32_e32 v154, v42
	v_exp_f32_e32 v155, v43
	v_mfma_f32_32x32x16_bf16 v[96:111], v[56:59], v[172:175], v[96:111]
	ds_read_b128 v[40:43], v156 offset:61440
	v_exp_f32_e32 v156, v44
	v_exp_f32_e32 v157, v45
	v_exp_f32_e32 v158, v46
	v_exp_f32_e32 v159, v47
	v_cvt_pk_bf16_f32 v44, v140, v141
	v_cvt_pk_bf16_f32 v45, v142, v143
	v_cvt_pk_bf16_f32 v46, v144, v145
	v_cvt_pk_bf16_f32 v47, v146, v147
	s_nop 1
	v_mfma_f32_32x32x16_bf16 v[80:95], v[60:63], v[44:47], v[80:95]
	v_xad_u32 v178, v206, 32, s48
	ds_read_b128 v[48:51], v178 offset:49152
	v_cvt_pk_bf16_f32 v52, v148, v149
	v_cvt_pk_bf16_f32 v53, v150, v151
	v_cvt_pk_bf16_f32 v54, v128, v129
	v_cvt_pk_bf16_f32 v55, v130, v131
	v_mfma_f32_32x32x16_bf16 v[64:79], v[32:35], v[44:47], v[64:79]
	ds_read_b128 v[56:59], v178 offset:53248
	v_pk_add_f32 v[62:63], v[146:147], v[142:143]
	v_pk_add_f32 v[60:61], v[144:145], v[140:141]
	s_waitcnt lgkmcnt(0)
	v_mfma_f32_32x32x16_bf16 v[16:31], v[36:39], v[44:47], v[16:31]
	ds_read_b128 v[32:35], v178 offset:57344
	v_add_f32_e64 v62, v150, v62
	v_add_f32_e64 v63, v151, v63
	v_add_f32_e64 v60, v148, v60
	v_add_f32_e64 v61, v149, v61
	v_pk_add_f32 v[62:63], v[130:131], v[62:63]
	v_pk_add_f32 v[60:61], v[128:129], v[60:61]
	v_mfma_f32_32x32x16_bf16 v[0:15], v[40:43], v[44:47], v[0:15]
	ds_read_b128 v[36:39], v178 offset:61440
	v_mfma_f32_32x32x16_bf16 v[80:95], v[48:51], v[52:55], v[80:95]
	v_xad_u32 v140, v206, 64, s48
	ds_read_b128 v[40:43], v140 offset:49152
	v_cvt_pk_bf16_f32 v44, v132, v133
	v_cvt_pk_bf16_f32 v45, v134, v135
	v_cvt_pk_bf16_f32 v46, v136, v137
	v_cvt_pk_bf16_f32 v47, v138, v139
	v_mfma_f32_32x32x16_bf16 v[64:79], v[56:59], v[52:55], v[64:79]
	ds_read_b128 v[48:51], v140 offset:53248
	v_add_f32_e64 v62, v134, v62
	v_add_f32_e64 v63, v135, v63
	v_add_f32_e64 v60, v132, v60
	v_add_f32_e64 v61, v133, v61
	v_pk_add_f32 v[62:63], v[138:139], v[62:63]
	v_pk_add_f32 v[60:61], v[136:137], v[60:61]
	s_waitcnt lgkmcnt(0)
	v_mfma_f32_32x32x16_bf16 v[16:31], v[32:35], v[52:55], v[16:31]
	ds_read_b128 v[56:59], v140 offset:57344
	v_add_f32_e64 v62, v154, v62
	v_add_f32_e64 v63, v155, v63
	v_add_f32_e64 v60, v152, v60
	v_add_f32_e64 v61, v153, v61
	v_pk_add_f32 v[130:131], v[158:159], v[62:63]
	v_pk_add_f32 v[128:129], v[156:157], v[60:61]
	v_mfma_f32_32x32x16_bf16 v[0:15], v[36:39], v[52:55], v[0:15]
	ds_read_b128 v[32:35], v140 offset:61440
	v_mfma_f32_32x32x16_bf16 v[80:95], v[40:43], v[44:47], v[80:95]
	v_add_u32_e32 v60, s48, v209
	ds_read_b128 v[36:39], v60 offset:49152
	v_cvt_pk_bf16_f32 v52, v152, v153
	v_cvt_pk_bf16_f32 v53, v154, v155
	v_cvt_pk_bf16_f32 v54, v156, v157
	v_cvt_pk_bf16_f32 v55, v158, v159
	v_mfma_f32_32x32x16_bf16 v[64:79], v[48:51], v[44:47], v[64:79]
	ds_read_b128 v[40:43], v60 offset:53248
	s_waitcnt lgkmcnt(0)
	v_mfma_f32_32x32x16_bf16 v[16:31], v[56:59], v[44:47], v[16:31]
	ds_read_b128 v[48:51], v60 offset:57344
	v_mfma_f32_32x32x16_bf16 v[0:15], v[32:35], v[44:47], v[0:15]
	ds_read_b128 v[56:59], v60 offset:61440
	v_mfma_f32_32x32x16_bf16 v[80:95], v[36:39], v[52:55], v[80:95]
	v_mfma_f32_32x32x16_bf16 v[64:79], v[40:43], v[52:55], v[64:79]
	s_waitcnt lgkmcnt(0)
	v_mfma_f32_32x32x16_bf16 v[16:31], v[48:51], v[52:55], v[16:31]
	v_mfma_f32_32x32x16_bf16 v[0:15], v[56:59], v[52:55], v[0:15]
	s_waitcnt vmcnt(4) lgkmcnt(0)
	s_barrier
	s_mov_b32 s68, s40
	s_add_i32 s68, s68, s15
	s_mul_hi_i32 s69, s68, 0x600
	s_mulk_i32 s68, 0x600
	s_add_u32 s68, s12, s68
	s_addc_u32 s69, s13, s69
	s_add_i32 s49, s49, s57
	s_mov_b32 m0, s49
	s_nop 0
	global_load_lds_dwordx4 v198, s[68:69]
	s_add_i32 m0, s49, 0x400
	s_nop 0
	global_load_lds_dwordx4 v194, s[68:69]
	s_mov_b32 s44, s40
	s_add_i32 s44, s44, s15
	s_sub_i32 s44, s44, 64
	s_ashr_i32 s45, s44, 31
	s_lshl_b64 s[44:45], s[44:45], 1
	s_add_u32 s44, s39, s44
	s_addc_u32 s45, s67, s45
	s_and_b32 s49, s20, 0xc000
	s_add_i32 s49, s58, s49
	s_add_i32 m0, s49, 0xc000
	s_nop 0
	global_load_lds_dwordx4 v196, s[44:45]
	s_add_i32 m0, s49, 0xc400
	s_nop 0
	global_load_lds_dwordx4 v192, s[44:45]
	s_add_i32 s48, s48, 0xc000
	s_add_i32 s44, s41, 1
	s_cmp_lg_u32 s41, 2
	s_cselect_b32 s41, s44, 0
	s_lshl_b32 s44, s41, 14
	s_add_i32 s44, s44, 0
	v_exp_f32_e32 v144, v112
	v_add_u32_e32 v36, s44, v205
	ds_read_b128 v[32:35], v36
	ds_read_b128 v[36:39], v36 offset:8192
	s_waitcnt lgkmcnt(0)
	v_mfma_f32_32x32x16_bf16 v[48:63], v[32:35], v[160:163], 0
	v_xad_u32 v40, v205, 32, s44
	ds_read_b128 v[132:135], v40
	ds_read_b128 v[136:139], v40 offset:8192
	v_xad_u32 v32, v205, 64, s44
	ds_read_b128 v[140:143], v32
	v_exp_f32_e32 v145, v113
	v_exp_f32_e32 v146, v114
	v_exp_f32_e32 v147, v115
	ds_read_b128 v[112:115], v32 offset:8192
	v_mfma_f32_32x32x16_bf16 v[32:47], v[36:39], v[160:163], 0
	v_exp_f32_e32 v148, v116
	v_exp_f32_e32 v149, v117
	v_exp_f32_e32 v150, v118
	v_exp_f32_e32 v151, v119
	s_waitcnt lgkmcnt(0)
	v_mfma_f32_32x32x16_bf16 v[48:63], v[132:135], v[164:167], v[48:63]
	v_add_u32_e32 v156, s44, v213
	ds_read_b128 v[116:119], v156
	v_exp_f32_e32 v152, v120
	v_exp_f32_e32 v153, v121
	v_exp_f32_e32 v154, v122
	v_exp_f32_e32 v155, v123
	v_mfma_f32_32x32x16_bf16 v[32:47], v[136:139], v[164:167], v[32:47]
	ds_read_b128 v[120:123], v156 offset:8192
	v_exp_f32_e32 v156, v124
	v_exp_f32_e32 v157, v125
	v_exp_f32_e32 v158, v126
	v_exp_f32_e32 v159, v127
	v_mfma_f32_32x32x16_bf16 v[48:63], v[140:143], v[168:171], v[48:63]
	v_add_u32_e32 v132, s48, v206
	ds_read_b128 v[124:127], v132 offset:16384
	v_exp_f32_e32 v136, v96
	v_exp_f32_e32 v137, v97
	v_exp_f32_e32 v138, v98
	v_exp_f32_e32 v139, v99
	v_mfma_f32_32x32x16_bf16 v[32:47], v[112:115], v[168:171], v[32:47]
	ds_read_b128 v[96:99], v132 offset:20480
	v_exp_f32_e32 v140, v100
	v_exp_f32_e32 v141, v101
	v_exp_f32_e32 v142, v102
	v_exp_f32_e32 v143, v103
	s_waitcnt lgkmcnt(0)
	v_mfma_f32_32x32x16_bf16 v[48:63], v[116:119], v[172:175], v[48:63]
	ds_read_b128 v[100:103], v132 offset:24576
	v_exp_f32_e32 v178, v104
	v_exp_f32_e32 v179, v105
	v_exp_f32_e32 v180, v106
	v_exp_f32_e32 v181, v107
	v_mfma_f32_32x32x16_bf16 v[32:47], v[120:123], v[172:175], v[32:47]
	ds_read_b128 v[104:107], v132 offset:28672
	v_exp_f32_e32 v182, v108
	v_exp_f32_e32 v183, v109
	v_exp_f32_e32 v184, v110
	v_exp_f32_e32 v185, v111
	v_cvt_pk_bf16_f32 v108, v144, v145
	v_cvt_pk_bf16_f32 v109, v146, v147
	v_cvt_pk_bf16_f32 v110, v148, v149
	v_cvt_pk_bf16_f32 v111, v150, v151
	s_nop 1
	v_mfma_f32_32x32x16_bf16 v[80:95], v[124:127], v[108:111], v[80:95]
	v_xad_u32 v186, v206, 32, s48
	ds_read_b128 v[112:115], v186 offset:16384
	v_cvt_pk_bf16_f32 v116, v152, v153
	v_cvt_pk_bf16_f32 v117, v154, v155
	v_cvt_pk_bf16_f32 v118, v156, v157
	v_cvt_pk_bf16_f32 v119, v158, v159
	v_mfma_f32_32x32x16_bf16 v[64:79], v[96:99], v[108:111], v[64:79]
	ds_read_b128 v[120:123], v186 offset:20480
	v_pk_add_f32 v[126:127], v[150:151], v[146:147]
	v_pk_add_f32 v[124:125], v[148:149], v[144:145]
	s_waitcnt lgkmcnt(0)
	v_mfma_f32_32x32x16_bf16 v[16:31], v[100:103], v[108:111], v[16:31]
	ds_read_b128 v[132:135], v186 offset:24576
	v_add_f32_e64 v98, v154, v126
	v_add_f32_e64 v99, v155, v127
	v_add_f32_e64 v96, v152, v124
	v_add_f32_e64 v97, v153, v125
	v_pk_add_f32 v[98:99], v[158:159], v[98:99]
	v_pk_add_f32 v[96:97], v[156:157], v[96:97]
	v_mfma_f32_32x32x16_bf16 v[0:15], v[104:107], v[108:111], v[0:15]
	ds_read_b128 v[100:103], v186 offset:28672
	v_mfma_f32_32x32x16_bf16 v[80:95], v[112:115], v[116:119], v[80:95]
	v_xad_u32 v124, v206, 64, s48
	ds_read_b128 v[104:107], v124 offset:16384
	v_cvt_pk_bf16_f32 v108, v136, v137
	v_cvt_pk_bf16_f32 v109, v138, v139
	v_cvt_pk_bf16_f32 v110, v140, v141
	v_cvt_pk_bf16_f32 v111, v142, v143
	v_mfma_f32_32x32x16_bf16 v[64:79], v[120:123], v[116:119], v[64:79]
	ds_read_b128 v[112:115], v124 offset:20480
	v_add_f32_e64 v98, v138, v98
	v_add_f32_e64 v99, v139, v99
	v_add_f32_e64 v96, v136, v96
	v_add_f32_e64 v97, v137, v97
	v_pk_add_f32 v[98:99], v[142:143], v[98:99]
	v_pk_add_f32 v[96:97], v[140:141], v[96:97]
	s_waitcnt lgkmcnt(0)
	v_mfma_f32_32x32x16_bf16 v[16:31], v[132:135], v[116:119], v[16:31]
	ds_read_b128 v[120:123], v124 offset:24576
	v_add_f32_e64 v98, v180, v98
	v_add_f32_e64 v99, v181, v99
	v_add_f32_e64 v96, v178, v96
	v_add_f32_e64 v97, v179, v97
	v_pk_add_f32 v[98:99], v[184:185], v[98:99]
	v_pk_add_f32 v[96:97], v[182:183], v[96:97]
	v_mfma_f32_32x32x16_bf16 v[0:15], v[100:103], v[116:119], v[0:15]
	ds_read_b128 v[124:127], v124 offset:28672
	v_mfma_f32_32x32x16_bf16 v[80:95], v[104:107], v[108:111], v[80:95]
	v_add_u32_e32 v132, s48, v209
	ds_read_b128 v[100:103], v132 offset:16384
	v_cvt_pk_bf16_f32 v116, v178, v179
	v_cvt_pk_bf16_f32 v117, v180, v181
	v_cvt_pk_bf16_f32 v118, v182, v183
	v_cvt_pk_bf16_f32 v119, v184, v185
	v_mfma_f32_32x32x16_bf16 v[64:79], v[112:115], v[108:111], v[64:79]
	ds_read_b128 v[104:107], v132 offset:20480
	s_waitcnt lgkmcnt(0)
	v_mfma_f32_32x32x16_bf16 v[16:31], v[120:123], v[108:111], v[16:31]
	ds_read_b128 v[112:115], v132 offset:24576
	v_mfma_f32_32x32x16_bf16 v[0:15], v[124:127], v[108:111], v[0:15]
	ds_read_b128 v[120:123], v132 offset:28672
	v_mfma_f32_32x32x16_bf16 v[80:95], v[100:103], v[116:119], v[80:95]
	v_mfma_f32_32x32x16_bf16 v[64:79], v[104:107], v[116:119], v[64:79]
	s_waitcnt lgkmcnt(0)
	v_mfma_f32_32x32x16_bf16 v[16:31], v[112:115], v[116:119], v[16:31]
	v_mfma_f32_32x32x16_bf16 v[0:15], v[120:123], v[116:119], v[0:15]
	s_waitcnt vmcnt(4) lgkmcnt(0)
	v_add_f32_e32 v100, v128, v129
	v_add_f32_e32 v101, v130, v131
	v_add_f32_e32 v100, v100, v101
	v_add_f32_e32 v96, v96, v97
	v_add_f32_e32 v97, v98, v99
	s_barrier
	v_add_f32_e32 v100, v177, v100
	v_add_f32_e32 v96, v96, v97
	v_add_f32_e32 v177, v100, v96
	s_add_i32 s21, s21, 2
	s_addk_i32 s15, 0x80
	s_add_i32 s20, s20, 0x8000
	s_branch .LBB0_936
.Lst1:
	s_mov_b32 s44, s40
	s_add_i32 s44, s44, s41
	s_sub_i32 s44, s44, 64
	s_mul_hi_i32 s45, s44, 0x600
	s_mulk_i32 s44, 0x600
	s_add_u32 s44, s14, s44
	s_addc_u32 s45, s15, s45
	s_lshl_b32 s49, s48, 14
	s_add_i32 s49, s58, s49
	s_mov_b32 m0, s49
	s_nop 0
	global_load_lds_dwordx4 v198, s[44:45]
	s_add_i32 m0, s49, 0x400
	s_nop 0
	global_load_lds_dwordx4 v194, s[44:45]
	s_mov_b32 s44, s40
	s_add_i32 s44, s44, s41
	s_addk_i32 s44, 0xff80
	s_ashr_i32 s45, s44, 31
	s_lshl_b64 s[44:45], s[44:45], 1
	s_add_u32 s44, s39, s44
	s_addc_u32 s45, s67, s45
	s_add_i32 s49, s46, 0xffffc000
	s_and_b32 s49, s49, 0xc000
	s_add_i32 s49, s58, s49
	s_add_i32 m0, s49, 0xc000
	global_load_lds_dwordx4 v196, s[44:45]
	v_lshl_add_u64 v[140:141], s[44:45], 0, v[192:193]
	s_add_i32 m0, s49, 0xc400
	s_add_i32 s44, s48, 1
	global_load_lds_dwordx4 v[140:141], off
	s_cmp_lg_u32 s48, 2
	s_cselect_b32 s48, s44, 0
	s_lshl_b32 s44, s48, 14
	s_and_b32 s49, s46, 0xc000
	s_add_i32 s68, s44, 0
	s_add_i32 s44, s49, 0
	v_add_u32_e32 v156, s44, v206
	ds_read_b128 v[140:143], v156 offset:49152
	ds_read_b128 v[148:151], v156 offset:53248
	ds_read_b128 v[152:155], v156 offset:57344
	ds_read_b128 v[156:159], v156 offset:61440
	s_waitcnt lgkmcnt(0)
	v_mfma_f32_32x32x16_bf16 v[80:95], v[140:143], v[144:147], v[80:95]
	v_xad_u32 v177, v206, 32, s44
	ds_read_b128 v[140:143], v177 offset:49152
	v_mfma_f32_32x32x16_bf16 v[64:79], v[148:151], v[144:147], v[64:79]
	ds_read_b128 v[148:151], v177 offset:53248
	v_mfma_f32_32x32x16_bf16 v[16:31], v[152:155], v[144:147], v[16:31]
	ds_read_b128 v[152:155], v177 offset:57344
	v_mfma_f32_32x32x16_bf16 v[0:15], v[156:159], v[144:147], v[0:15]
	ds_read_b128 v[144:147], v177 offset:61440
	s_waitcnt lgkmcnt(0)
	v_mfma_f32_32x32x16_bf16 v[80:95], v[140:143], v[128:131], v[80:95]
	v_xad_u32 v156, v206, 64, s44
	ds_read_b128 v[140:143], v156 offset:49152
	v_mfma_f32_32x32x16_bf16 v[64:79], v[148:151], v[128:131], v[64:79]
	ds_read_b128 v[148:151], v156 offset:53248
	v_mfma_f32_32x32x16_bf16 v[16:31], v[152:155], v[128:131], v[16:31]
	ds_read_b128 v[152:155], v156 offset:57344
	v_mfma_f32_32x32x16_bf16 v[0:15], v[144:147], v[128:131], v[0:15]
	ds_read_b128 v[128:131], v156 offset:61440
	s_waitcnt lgkmcnt(0)
	v_mfma_f32_32x32x16_bf16 v[80:95], v[140:143], v[132:135], v[80:95]
	v_add_u32_e32 v156, s44, v209
	ds_read_b128 v[140:143], v156 offset:49152
	v_mfma_f32_32x32x16_bf16 v[64:79], v[148:151], v[132:135], v[64:79]
	ds_read_b128 v[144:147], v156 offset:53248
	v_mfma_f32_32x32x16_bf16 v[16:31], v[152:155], v[132:135], v[16:31]
	ds_read_b128 v[148:151], v156 offset:57344
	v_mfma_f32_32x32x16_bf16 v[0:15], v[128:131], v[132:135], v[0:15]
	ds_read_b128 v[128:131], v156 offset:61440
	s_waitcnt lgkmcnt(0)
	v_mfma_f32_32x32x16_bf16 v[80:95], v[140:143], v[136:139], v[80:95]
	v_add_u32_e32 v140, s68, v205
	ds_read_b128 v[132:135], v140
	v_mfma_f32_32x32x16_bf16 v[64:79], v[144:147], v[136:139], v[64:79]
	ds_read_b128 v[140:143], v140 offset:8192
	v_mfma_f32_32x32x16_bf16 v[16:31], v[148:151], v[136:139], v[16:31]
	v_xad_u32 v144, v205, 32, s68
	ds_read_b128 v[176:179], v144
	v_mfma_f32_32x32x16_bf16 v[0:15], v[128:131], v[136:139], v[0:15]
	ds_read_b128 v[182:185], v144 offset:8192
	s_waitcnt lgkmcnt(0)
	v_mfma_f32_32x32x16_bf16 v[144:159], v[132:135], v[160:163], 0
	v_xad_u32 v216, v205, 64, s68
	ds_read_b128 v[186:189], v216
	v_exp_f32_e32 v220, v112
	v_exp_f32_e32 v221, v113
	v_exp_f32_e32 v222, v114
	v_exp_f32_e32 v223, v115
	v_mfma_f32_32x32x16_bf16 v[128:143], v[140:143], v[160:163], 0
	ds_read_b128 v[216:219], v216 offset:8192
	v_exp_f32_e32 v224, v116
	v_exp_f32_e32 v225, v117
	v_exp_f32_e32 v226, v118
	v_exp_f32_e32 v227, v119
	v_mfma_f32_32x32x16_bf16 v[144:159], v[176:179], v[164:167], v[144:159]
	v_add_u32_e32 v181, s68, v213
	ds_read_b128 v[116:119], v181
	v_exp_f32_e32 v228, v120
	v_exp_f32_e32 v229, v121
	v_exp_f32_e32 v230, v122
	v_exp_f32_e32 v231, v123
	v_cvt_pk_bf16_f32 v112, v220, v221
	v_cvt_pk_bf16_f32 v113, v222, v223
	v_cvt_pk_bf16_f32 v114, v224, v225
	v_cvt_pk_bf16_f32 v115, v226, v227
	v_pk_add_f32 v[122:123], v[226:227], v[222:223]
	v_pk_add_f32 v[120:121], v[224:225], v[220:221]
	v_mfma_f32_32x32x16_bf16 v[128:143], v[182:185], v[164:167], v[128:143]
	ds_read_b128 v[176:179], v181 offset:8192
	v_exp_f32_e32 v124, v124
	v_exp_f32_e32 v125, v125
	v_exp_f32_e32 v126, v126
	v_exp_f32_e32 v127, v127
	s_waitcnt lgkmcnt(0)
	v_mfma_f32_32x32x16_bf16 v[144:159], v[186:189], v[168:171], v[144:159]
	v_add_f32_e64 v122, v230, v122
	v_add_f32_e64 v123, v231, v123
	v_add_f32_e64 v120, v228, v120
	v_add_f32_e64 v121, v229, v121
	v_exp_f32_e32 v182, v96
	v_exp_f32_e32 v183, v97
	v_exp_f32_e32 v184, v98
	v_exp_f32_e32 v185, v99
	v_cvt_pk_bf16_f32 v96, v228, v229
	v_cvt_pk_bf16_f32 v97, v230, v231
	v_cvt_pk_bf16_f32 v98, v124, v125
	v_cvt_pk_bf16_f32 v99, v126, v127
	v_pk_add_f32 v[122:123], v[126:127], v[122:123]
	v_pk_add_f32 v[120:121], v[124:125], v[120:121]
	v_mfma_f32_32x32x16_bf16 v[128:143], v[216:219], v[168:171], v[128:143]
	v_exp_f32_e32 v124, v100
	v_exp_f32_e32 v125, v101
	v_exp_f32_e32 v126, v102
	v_exp_f32_e32 v127, v103
	v_mfma_f32_32x32x16_bf16 v[144:159], v[116:119], v[172:175], v[144:159]
	v_exp_f32_e32 v186, v104
	v_exp_f32_e32 v187, v105
	v_exp_f32_e32 v188, v106
	v_exp_f32_e32 v189, v107
	v_pk_add_f32 v[106:107], v[184:185], v[122:123]
	v_pk_add_f32 v[104:105], v[182:183], v[120:121]
	v_cvt_pk_bf16_f32 v100, v182, v183
	v_cvt_pk_bf16_f32 v101, v184, v185
	v_cvt_pk_bf16_f32 v102, v124, v125
	v_cvt_pk_bf16_f32 v103, v126, v127
	v_pk_add_f32 v[118:119], v[126:127], v[106:107]
	v_pk_add_f32 v[116:117], v[124:125], v[104:105]
	v_mfma_f32_32x32x16_bf16 v[128:143], v[176:179], v[172:175], v[128:143]
	v_exp_f32_e32 v120, v108
	v_exp_f32_e32 v121, v109
	v_exp_f32_e32 v122, v110
	v_exp_f32_e32 v123, v111
	v_pk_add_f32 v[110:111], v[188:189], v[118:119]
	v_pk_add_f32 v[108:109], v[186:187], v[116:117]
	v_cvt_pk_bf16_f32 v104, v186, v187
	v_cvt_pk_bf16_f32 v105, v188, v189
	v_cvt_pk_bf16_f32 v106, v120, v121
	v_cvt_pk_bf16_f32 v107, v122, v123
	v_pk_add_f32 v[178:179], v[122:123], v[110:111]
	v_pk_add_f32 v[176:177], v[120:121], v[108:109]
	s_waitcnt vmcnt(4) lgkmcnt(0)
	s_barrier
	s_mov_b32 s69, s40
	s_add_i32 s69, s69, s41
	s_mul_hi_i32 s71, s69, 0x600
	s_mulk_i32 s69, 0x600
	s_add_u32 s70, s14, s69
	s_addc_u32 s71, s15, s71
	s_add_i32 s68, s68, s57
	s_mov_b32 m0, s68
	s_nop 0
	global_load_lds_dwordx4 v198, s[70:71]
	s_add_i32 m0, s68, 0x400
	s_nop 0
	global_load_lds_dwordx4 v194, s[70:71]
	s_mov_b32 s2, s40
	s_add_i32 s2, s2, s41
	s_sub_i32 s2, s2, 64
	s_ashr_i32 s3, s2, 31
	s_lshl_b64 s[2:3], s[2:3], 1
	s_add_u32 s2, s39, s2
	s_addc_u32 s3, s67, s3
	s_add_i32 s49, s58, s49
	s_add_i32 m0, s49, 0xc000
	s_nop 0
	global_load_lds_dwordx4 v196, s[2:3]
	s_add_i32 m0, s49, 0xc400
	s_nop 0
	global_load_lds_dwordx4 v192, s[2:3]
	s_add_i32 s2, s46, 0xffff4000
	s_add_i32 s3, s48, 1
	s_cmp_lg_u32 s48, 2
	s_cselect_b32 s48, s3, 0
	s_and_b32 s2, s2, 0xc000
	s_add_i32 s2, s2, 0
	s_lshl_b32 s3, s48, 14
	v_add_u32_e32 v124, s2, v206
	ds_read_b128 v[108:111], v124 offset:49152
	ds_read_b128 v[116:119], v124 offset:53248
	ds_read_b128 v[120:123], v124 offset:57344
	ds_read_b128 v[124:127], v124 offset:61440
	s_waitcnt lgkmcnt(0)
	v_mfma_f32_32x32x16_bf16 v[80:95], v[108:111], v[112:115], v[80:95]
	v_xad_u32 v182, v206, 32, s2
	ds_read_b128 v[108:111], v182 offset:49152
	s_add_i32 s3, s3, 0
	v_mfma_f32_32x32x16_bf16 v[64:79], v[116:119], v[112:115], v[64:79]
	ds_read_b128 v[116:119], v182 offset:53248
	v_mfma_f32_32x32x16_bf16 v[16:31], v[120:123], v[112:115], v[16:31]
	ds_read_b128 v[120:123], v182 offset:57344
	v_mfma_f32_32x32x16_bf16 v[0:15], v[124:127], v[112:115], v[0:15]
	ds_read_b128 v[112:115], v182 offset:61440
	s_waitcnt lgkmcnt(0)
	v_mfma_f32_32x32x16_bf16 v[80:95], v[108:111], v[96:99], v[80:95]
	v_xad_u32 v124, v206, 64, s2
	ds_read_b128 v[108:111], v124 offset:49152
	v_mfma_f32_32x32x16_bf16 v[64:79], v[116:119], v[96:99], v[64:79]
	ds_read_b128 v[116:119], v124 offset:53248
	v_mfma_f32_32x32x16_bf16 v[16:31], v[120:123], v[96:99], v[16:31]
	ds_read_b128 v[120:123], v124 offset:57344
	v_mfma_f32_32x32x16_bf16 v[0:15], v[112:115], v[96:99], v[0:15]
	ds_read_b128 v[96:99], v124 offset:61440
	s_waitcnt lgkmcnt(0)
	v_mfma_f32_32x32x16_bf16 v[80:95], v[108:111], v[100:103], v[80:95]
	v_add_u32_e32 v124, s2, v209
	ds_read_b128 v[108:111], v124 offset:49152
	v_mfma_f32_32x32x16_bf16 v[64:79], v[116:119], v[100:103], v[64:79]
	ds_read_b128 v[112:115], v124 offset:53248
	v_mfma_f32_32x32x16_bf16 v[16:31], v[120:123], v[100:103], v[16:31]
	ds_read_b128 v[116:119], v124 offset:57344
	v_mfma_f32_32x32x16_bf16 v[0:15], v[96:99], v[100:103], v[0:15]
	ds_read_b128 v[120:123], v124 offset:61440
	s_waitcnt lgkmcnt(0)
	v_mfma_f32_32x32x16_bf16 v[80:95], v[108:111], v[104:107], v[80:95]
	v_add_u32_e32 v100, s3, v205
	ds_read_b128 v[96:99], v100
	v_mfma_f32_32x32x16_bf16 v[64:79], v[112:115], v[104:107], v[64:79]
	ds_read_b128 v[100:103], v100 offset:8192
	v_mfma_f32_32x32x16_bf16 v[16:31], v[116:119], v[104:107], v[16:31]
	v_xad_u32 v108, v205, 32, s3
	ds_read_b128 v[182:185], v108
	v_mfma_f32_32x32x16_bf16 v[0:15], v[120:123], v[104:107], v[0:15]
	ds_read_b128 v[186:189], v108 offset:8192
	s_waitcnt lgkmcnt(0)
	v_mfma_f32_32x32x16_bf16 v[112:127], v[96:99], v[160:163], 0
	v_xad_u32 v104, v205, 64, s3
	ds_read_b128 v[216:219], v104
	v_exp_f32_e32 v224, v144
	v_exp_f32_e32 v225, v145
	v_exp_f32_e32 v226, v146
	v_exp_f32_e32 v227, v147
	ds_read_b128 v[220:223], v104 offset:8192
	v_mfma_f32_32x32x16_bf16 v[96:111], v[100:103], v[160:163], 0
	v_exp_f32_e32 v228, v148
	v_exp_f32_e32 v229, v149
	v_exp_f32_e32 v230, v150
	v_exp_f32_e32 v231, v151
	v_mfma_f32_32x32x16_bf16 v[112:127], v[182:185], v[164:167], v[112:127]
	v_add_u32_e32 v181, s3, v213
	ds_read_b128 v[148:151], v181
	v_exp_f32_e32 v232, v152
	v_exp_f32_e32 v233, v153
	v_exp_f32_e32 v234, v154
	v_exp_f32_e32 v235, v155
	v_cvt_pk_bf16_f32 v144, v224, v225
	v_cvt_pk_bf16_f32 v145, v226, v227
	v_cvt_pk_bf16_f32 v146, v228, v229
	v_cvt_pk_bf16_f32 v147, v230, v231
	v_pk_add_f32 v[154:155], v[230:231], v[226:227]
	v_pk_add_f32 v[152:153], v[228:229], v[224:225]
	v_mfma_f32_32x32x16_bf16 v[96:111], v[186:189], v[164:167], v[96:111]
	ds_read_b128 v[182:185], v181 offset:8192
	v_exp_f32_e32 v156, v156
	v_exp_f32_e32 v157, v157
	v_exp_f32_e32 v158, v158
	v_exp_f32_e32 v159, v159
	s_waitcnt lgkmcnt(0)
	v_mfma_f32_32x32x16_bf16 v[112:127], v[216:219], v[168:171], v[112:127]
	v_add_f32_e64 v154, v234, v154
	v_add_f32_e64 v155, v235, v155
	v_add_f32_e64 v152, v232, v152
	v_add_f32_e64 v153, v233, v153
	v_exp_f32_e32 v186, v128
	v_exp_f32_e32 v187, v129
	v_exp_f32_e32 v188, v130
	v_exp_f32_e32 v189, v131
	v_cvt_pk_bf16_f32 v128, v232, v233
	v_cvt_pk_bf16_f32 v129, v234, v235
	v_cvt_pk_bf16_f32 v130, v156, v157
	v_cvt_pk_bf16_f32 v131, v158, v159
	v_pk_add_f32 v[154:155], v[158:159], v[154:155]
	v_pk_add_f32 v[152:153], v[156:157], v[152:153]
	v_mfma_f32_32x32x16_bf16 v[96:111], v[220:223], v[168:171], v[96:111]
	v_exp_f32_e32 v156, v132
	v_exp_f32_e32 v157, v133
	v_exp_f32_e32 v158, v134
	v_exp_f32_e32 v159, v135
	v_mfma_f32_32x32x16_bf16 v[112:127], v[148:151], v[172:175], v[112:127]
	v_exp_f32_e32 v216, v136
	v_exp_f32_e32 v217, v137
	v_exp_f32_e32 v218, v138
	v_exp_f32_e32 v219, v139
	v_pk_add_f32 v[138:139], v[188:189], v[154:155]
	v_pk_add_f32 v[136:137], v[186:187], v[152:153]
	v_cvt_pk_bf16_f32 v132, v186, v187
	v_cvt_pk_bf16_f32 v133, v188, v189
	v_cvt_pk_bf16_f32 v134, v156, v157
	v_cvt_pk_bf16_f32 v135, v158, v159
	v_pk_add_f32 v[150:151], v[158:159], v[138:139]
	v_pk_add_f32 v[148:149], v[156:157], v[136:137]
	v_mfma_f32_32x32x16_bf16 v[96:111], v[182:185], v[172:175], v[96:111]
	v_exp_f32_e32 v152, v140
	v_exp_f32_e32 v153, v141
	v_exp_f32_e32 v154, v142
	v_exp_f32_e32 v155, v143
	v_pk_add_f32 v[142:143], v[218:219], v[150:151]
	v_pk_add_f32 v[140:141], v[216:217], v[148:149]
	v_cvt_pk_bf16_f32 v136, v216, v217
	v_cvt_pk_bf16_f32 v137, v218, v219
	v_cvt_pk_bf16_f32 v138, v152, v153
	v_cvt_pk_bf16_f32 v139, v154, v155
	v_pk_add_f32 v[142:143], v[154:155], v[142:143]
	v_pk_add_f32 v[140:141], v[152:153], v[140:141]
	s_waitcnt vmcnt(4) lgkmcnt(0)
	v_add_f32_e32 v148, v176, v177
	v_add_f32_e32 v149, v178, v179
	v_add_f32_e32 v148, v148, v149
	v_add_f32_e32 v140, v140, v141
	v_add_f32_e32 v141, v142, v143
	s_barrier
	v_add_f32_e32 v148, v180, v148
	v_add_f32_e32 v140, v140, v141
	v_add_f32_e32 v180, v148, v140
	s_add_i32 s47, s47, 2
	s_addk_i32 s41, 0x80
	s_add_i32 s46, s46, 0x8000
	s_branch .LBB0_914
